# weight-conversion job 3 (second FFN w2) moved from P1's half-round tail to P9's (P1's conversion half was the critical path)
# baseline (speedup 1.0000x reference)
.LBB0_118:
	s_sub_i32 s3, s2, s85
	s_cmp_lt_i32 s3, 0
	s_cselect_b64 s[4:5], -1, 0
	s_cmp_ge_i32 s2, s60
	s_cselect_b64 s[6:7], -1, 0
	s_or_b64 s[4:5], s[6:7], s[4:5]
	s_and_b64 vcc, exec, s[4:5]
	s_cbranch_vccnz .LBB0_367
	v_readlane_b32 s5, v242, 37
	s_mul_i32 s4, s5, 0x4200
	s_lshl_b32 s3, s3, 3
	s_sub_i32 s13, s60, s85
	s_add_i32 s12, s4, 0
	s_add_i32 s3, s3, s5
	s_cmpk_gt_i32 s3, 0x83f
	s_cbranch_scc1 .LBB0_243
	v_readlane_b32 s16, v242, 40
	s_lshl_b32 s14, s13, 3
	v_readlane_b32 s26, v242, 50
	v_readlane_b32 s27, v242, 51
	s_add_u32 s26, s26, 0x1600000
	v_readlane_b32 s24, v242, 48
	s_addc_u32 s27, s27, 0
	v_readlane_b32 s25, v242, 49
	s_add_u32 s62, s24, 0x1000
	s_addc_u32 s63, s25, 0
	s_add_u32 s64, s76, 0x4280000
	s_addc_u32 s65, s77, 0
	s_add_u32 s24, s76, 0x4080000
	v_readlane_b32 s44, v242, 3
	s_addc_u32 s25, s77, 0
	v_readlane_b32 s52, v242, 11
	v_readlane_b32 s53, v242, 12
	s_add_u32 s10, s52, 0x1000
	s_addc_u32 s11, s53, 0
	s_add_u32 s66, s76, 0x3e80000
	s_addc_u32 s67, s77, 0
	s_add_u32 s70, s76, 0x3d80000
	s_addc_u32 s71, s77, 0
	s_add_u32 s72, s76, 0x3980000
	v_readlane_b32 s50, v242, 9
	s_addc_u32 s73, s77, 0
	v_readlane_b32 s51, v242, 10
	s_add_u32 s34, s50, 0xb00000
	s_addc_u32 s35, s51, 0
	s_add_u32 s88, s76, 0x3400000
	v_readlane_b32 s48, v242, 7
	s_addc_u32 s89, s77, 0
	v_readlane_b32 s49, v242, 8
	s_add_u32 s6, s48, 0x1600000
	s_addc_u32 s7, s49, 0
	s_add_u32 s92, s76, 0x2900000
	v_readlane_b32 s46, v242, 5
	s_addc_u32 s93, s77, 0
	v_readlane_b32 s47, v242, 6
	s_add_u32 s94, s46, 0x1000
	s_addc_u32 s95, s47, 0
	s_add_u32 s96, s76, 0x2500000
	s_addc_u32 s97, s77, 0
	s_add_u32 s80, s76, 0x1f80000
	s_addc_u32 s81, s77, 0
	s_add_u32 s40, s76, 0x1480000
	s_addc_u32 s41, s77, 0
	v_lshlrev_b32_e32 v0, 2, v184
	s_add_u32 s4, s76, 0xf00000
	v_and_b32_e32 v69, 60, v0
	v_readlane_b32 s28, v242, 52
	s_addc_u32 s5, s77, 0
	v_and_b32_e32 v70, 28, v0
	v_lshlrev_b32_e32 v0, 3, v185
	v_lshrrev_b32_e32 v68, 4, v184
	v_readlane_b32 s29, v242, 53
	s_add_u32 s8, s28, 0xb00000
	v_lshrrev_b32_e32 v71, 3, v184
	v_and_b32_e32 v0, 56, v0
	s_addc_u32 s9, s29, 0
	v_lshl_add_u32 v1, v69, 2, s12
	v_mul_u32_u24_e32 v2, 0x104, v68
	v_mul_u32_u24_e32 v3, 0x104, v0
	v_lshlrev_b32_e32 v4, 2, v71
	v_readlane_b32 s17, v242, 41
	v_readlane_b32 s18, v242, 42
	v_readlane_b32 s19, v242, 43
	v_readlane_b32 s20, v242, 44
	v_readlane_b32 s21, v242, 45
	v_readlane_b32 s22, v242, 46
	v_readlane_b32 s23, v242, 47
	v_readlane_b32 s30, v242, 54
	v_readlane_b32 s31, v242, 55
	v_readlane_b32 s45, v242, 4
	v_readlane_b32 s54, v242, 13
	v_readlane_b32 s55, v242, 14
	v_readlane_b32 s56, v242, 15
	v_readlane_b32 s57, v242, 16
	v_readlane_b32 s58, v242, 17
	v_readlane_b32 s59, v242, 18
	v_writelane_b32 v242, s8, 60
	s_mov_b64 s[28:29], s[6:7]
	v_mov_b32_e32 v65, 0
	v_add3_u32 v72, s12, v3, v4
	v_or_b32_e32 v73, 8, v71
	v_or_b32_e32 v74, 16, v71
	v_or_b32_e32 v75, 24, v71
	v_or_b32_e32 v76, 32, v71
	v_or_b32_e32 v77, 40, v71
	v_or_b32_e32 v78, 48, v71
	v_or_b32_e32 v79, 56, v71
	v_add_u32_e32 v80, v1, v2
	v_lshlrev_b32_e32 v64, 1, v0
	s_mov_b32 s15, s3
	v_writelane_b32 v242, s9, 61
	s_branch .LBB0_122
.LBB0_121:
	s_waitcnt vmcnt(15)
	ds_write2_b32 v80, v60, v61 offset1:1
	ds_write2_b32 v80, v62, v63 offset0:2 offset1:3
	v_add_u32_e32 v60, 0x410, v80
	s_waitcnt vmcnt(14)
	ds_write2_b32 v60, v56, v57 offset1:1
	v_add_u32_e32 v56, 0x418, v80
	ds_write2_b32 v56, v58, v59 offset1:1
	v_add_u32_e32 v56, 0x820, v80
	s_waitcnt vmcnt(13)
	ds_write2_b32 v56, v52, v53 offset1:1
	v_add_u32_e32 v52, 0x828, v80
	ds_write2_b32 v52, v54, v55 offset1:1
	v_add_u32_e32 v52, 0xc30, v80
	s_waitcnt vmcnt(12)
	ds_write2_b32 v52, v48, v49 offset1:1
	v_add_u32_e32 v48, 0xc38, v80
	ds_write2_b32 v48, v50, v51 offset1:1
	v_add_u32_e32 v48, 0x1040, v80
	s_waitcnt vmcnt(11)
	ds_write2_b32 v48, v44, v45 offset1:1
	v_add_u32_e32 v44, 0x1048, v80
	ds_write2_b32 v44, v46, v47 offset1:1
	v_add_u32_e32 v44, 0x1450, v80
	s_waitcnt vmcnt(10)
	ds_write2_b32 v44, v40, v41 offset1:1
	v_add_u32_e32 v40, 0x1458, v80
	ds_write2_b32 v40, v42, v43 offset1:1
	v_add_u32_e32 v40, 0x1860, v80
	s_waitcnt vmcnt(9)
	ds_write2_b32 v40, v36, v37 offset1:1
	v_add_u32_e32 v36, 0x1868, v80
	ds_write2_b32 v36, v38, v39 offset1:1
	v_add_u32_e32 v36, 0x1c70, v80
	s_waitcnt vmcnt(8)
	ds_write2_b32 v36, v32, v33 offset1:1
	v_add_u32_e32 v32, 0x1c78, v80
	ds_write2_b32 v32, v34, v35 offset1:1
	v_add_u32_e32 v32, 0x2080, v80
	s_waitcnt vmcnt(7)
	ds_write2_b32 v32, v28, v29 offset1:1
	v_add_u32_e32 v28, 0x2088, v80
	ds_write2_b32 v28, v30, v31 offset1:1
	v_add_u32_e32 v28, 0x2490, v80
	s_waitcnt vmcnt(6)
	ds_write2_b32 v28, v24, v25 offset1:1
	v_add_u32_e32 v24, 0x2498, v80
	ds_write2_b32 v24, v26, v27 offset1:1
	v_add_u32_e32 v24, 0x28a0, v80
	s_waitcnt vmcnt(5)
	ds_write2_b32 v24, v20, v21 offset1:1
	v_add_u32_e32 v20, 0x28a8, v80
	ds_write2_b32 v20, v22, v23 offset1:1
	v_add_u32_e32 v20, 0x2cb0, v80
	s_waitcnt vmcnt(4)
	ds_write2_b32 v20, v16, v17 offset1:1
	v_add_u32_e32 v16, 0x2cb8, v80
	ds_write2_b32 v16, v18, v19 offset1:1
	v_add_u32_e32 v16, 0x30c0, v80
	s_waitcnt vmcnt(3)
	ds_write2_b32 v16, v12, v13 offset1:1
	v_add_u32_e32 v12, 0x30c8, v80
	ds_write2_b32 v12, v14, v15 offset1:1
	v_add_u32_e32 v12, 0x34d0, v80
	s_waitcnt vmcnt(2)
	ds_write2_b32 v12, v8, v9 offset1:1
	v_add_u32_e32 v8, 0x34d8, v80
	ds_write2_b32 v8, v10, v11 offset1:1
	v_add_u32_e32 v8, 0x38e0, v80
	s_waitcnt vmcnt(1)
	ds_write2_b32 v8, v4, v5 offset1:1
	v_add_u32_e32 v4, 0x38e8, v80
	ds_write2_b32 v4, v6, v7 offset1:1
	v_add_u32_e32 v4, 0x3cf0, v80
	s_waitcnt vmcnt(0)
	ds_write2_b32 v4, v0, v1 offset1:1
	v_add_u32_e32 v0, 0x3cf8, v80
	ds_write2_b32 v0, v2, v3 offset1:1
	s_waitcnt lgkmcnt(0)
	ds_read2_b32 v[4:5], v72 offset0:65 offset1:73
	ds_read2_b32 v[6:7], v72 offset1:8
	ds_read2_b32 v[8:9], v72 offset0:130 offset1:138
	ds_read2_b32 v[10:11], v72 offset0:195 offset1:203
	v_add_u32_e32 v22, 0x400, v72
	ds_read2_b32 v[12:13], v22 offset0:4 offset1:12
	ds_read2_b32 v[14:15], v22 offset0:69 offset1:77
	ds_read2_b32 v[16:17], v22 offset0:134 offset1:142
	ds_read2_b32 v[18:19], v22 offset0:199 offset1:207
	s_waitcnt lgkmcnt(6)
	v_cvt_pk_bf16_f32 v0, v6, v4
	v_or_b32_e32 v4, s16, v71
	s_ashr_i32 s17, s16, 31
	v_mul_lo_u32 v6, s9, v4
	s_mul_i32 s17, s8, s17
	v_mad_u64_u32 v[20:21], s[18:19], s8, v4, 0
	s_ashr_i32 s87, s86, 31
	v_add3_u32 v21, v21, s17, v6
	v_lshl_add_u64 v[20:21], v[20:21], 1, s[6:7]
	s_lshl_b64 s[30:31], s[86:87], 1
	v_lshl_add_u64 v[20:21], v[20:21], 0, s[30:31]
	s_waitcnt lgkmcnt(4)
	v_cvt_pk_bf16_f32 v1, v8, v10
	s_waitcnt lgkmcnt(2)
	v_cvt_pk_bf16_f32 v2, v12, v14
	s_waitcnt lgkmcnt(0)
	v_cvt_pk_bf16_f32 v3, v16, v18
	v_lshl_add_u64 v[20:21], v[20:21], 0, v[64:65]
	v_or_b32_e32 v4, s16, v73
	global_store_dwordx4 v[20:21], v[0:3], off
	v_mul_lo_u32 v6, s9, v4
	s_add_i32 s15, s15, s14
	v_cvt_pk_bf16_f32 v0, v7, v5
	v_mad_u64_u32 v[4:5], s[18:19], s8, v4, 0
	v_add3_u32 v5, v5, s17, v6
	v_lshl_add_u64 v[4:5], v[4:5], 1, s[6:7]
	v_lshl_add_u64 v[4:5], v[4:5], 0, s[30:31]
	v_cvt_pk_bf16_f32 v1, v9, v11
	v_cvt_pk_bf16_f32 v2, v13, v15
	v_cvt_pk_bf16_f32 v3, v17, v19
	v_lshl_add_u64 v[4:5], v[4:5], 0, v[64:65]
	ds_read2_b32 v[6:7], v72 offset0:16 offset1:24
	ds_read2_b32 v[8:9], v72 offset0:81 offset1:89
	ds_read2_b32 v[10:11], v72 offset0:146 offset1:154
	ds_read2_b32 v[12:13], v72 offset0:211 offset1:219
	ds_read2_b32 v[14:15], v22 offset0:20 offset1:28
	ds_read2_b32 v[16:17], v22 offset0:85 offset1:93
	ds_read2_b32 v[18:19], v22 offset0:150 offset1:158
	ds_read2_b32 v[20:21], v22 offset0:215 offset1:223
	global_store_dwordx4 v[4:5], v[0:3], off
	v_or_b32_e32 v4, s16, v74
	s_cmpk_lt_i32 s15, 0x840
	s_waitcnt lgkmcnt(6)
	v_cvt_pk_bf16_f32 v0, v6, v8
	v_mul_lo_u32 v6, s9, v4
	v_mad_u64_u32 v[4:5], s[18:19], s8, v4, 0
	v_add3_u32 v5, v5, s17, v6
	v_lshl_add_u64 v[4:5], v[4:5], 1, s[6:7]
	v_lshl_add_u64 v[4:5], v[4:5], 0, s[30:31]
	s_waitcnt lgkmcnt(4)
	v_cvt_pk_bf16_f32 v1, v10, v12
	s_waitcnt lgkmcnt(2)
	v_cvt_pk_bf16_f32 v2, v14, v16
	s_waitcnt lgkmcnt(0)
	v_cvt_pk_bf16_f32 v3, v18, v20
	v_lshl_add_u64 v[4:5], v[4:5], 0, v[64:65]
	global_store_dwordx4 v[4:5], v[0:3], off
	v_or_b32_e32 v4, s16, v75
	v_mul_lo_u32 v6, s9, v4
	v_mad_u64_u32 v[4:5], s[18:19], s8, v4, 0
	v_add3_u32 v5, v5, s17, v6
	v_lshl_add_u64 v[4:5], v[4:5], 1, s[6:7]
	v_lshl_add_u64 v[4:5], v[4:5], 0, s[30:31]
	v_cvt_pk_bf16_f32 v0, v7, v9
	v_cvt_pk_bf16_f32 v1, v11, v13
	v_cvt_pk_bf16_f32 v2, v15, v17
	v_cvt_pk_bf16_f32 v3, v19, v21
	v_lshl_add_u64 v[4:5], v[4:5], 0, v[64:65]
	ds_read2_b32 v[6:7], v72 offset0:32 offset1:40
	ds_read2_b32 v[8:9], v72 offset0:97 offset1:105
	ds_read2_b32 v[10:11], v72 offset0:162 offset1:170
	ds_read2_b32 v[12:13], v72 offset0:227 offset1:235
	ds_read2_b32 v[14:15], v22 offset0:36 offset1:44
	ds_read2_b32 v[16:17], v22 offset0:101 offset1:109
	ds_read2_b32 v[18:19], v22 offset0:166 offset1:174
	ds_read2_b32 v[20:21], v22 offset0:231 offset1:239
	global_store_dwordx4 v[4:5], v[0:3], off
	v_or_b32_e32 v4, s16, v76
	s_waitcnt lgkmcnt(6)
	v_cvt_pk_bf16_f32 v0, v6, v8
	v_mul_lo_u32 v6, s9, v4
	v_mad_u64_u32 v[4:5], s[18:19], s8, v4, 0
	v_add3_u32 v5, v5, s17, v6
	v_lshl_add_u64 v[4:5], v[4:5], 1, s[6:7]
	v_lshl_add_u64 v[4:5], v[4:5], 0, s[30:31]
	s_waitcnt lgkmcnt(4)
	v_cvt_pk_bf16_f32 v1, v10, v12
	s_waitcnt lgkmcnt(2)
	v_cvt_pk_bf16_f32 v2, v14, v16
	s_waitcnt lgkmcnt(0)
	v_cvt_pk_bf16_f32 v3, v18, v20
	v_lshl_add_u64 v[4:5], v[4:5], 0, v[64:65]
	global_store_dwordx4 v[4:5], v[0:3], off
	v_or_b32_e32 v4, s16, v77
	v_mul_lo_u32 v6, s9, v4
	v_mad_u64_u32 v[4:5], s[18:19], s8, v4, 0
	v_add3_u32 v5, v5, s17, v6
	v_lshl_add_u64 v[4:5], v[4:5], 1, s[6:7]
	v_lshl_add_u64 v[4:5], v[4:5], 0, s[30:31]
	v_cvt_pk_bf16_f32 v0, v7, v9
	v_cvt_pk_bf16_f32 v1, v11, v13
	v_cvt_pk_bf16_f32 v2, v15, v17
	v_cvt_pk_bf16_f32 v3, v19, v21
	v_lshl_add_u64 v[4:5], v[4:5], 0, v[64:65]
	ds_read2_b32 v[6:7], v72 offset0:48 offset1:56
	ds_read2_b32 v[8:9], v72 offset0:113 offset1:121
	ds_read2_b32 v[10:11], v72 offset0:178 offset1:186
	ds_read2_b32 v[12:13], v72 offset0:243 offset1:251
	ds_read2_b32 v[14:15], v22 offset0:52 offset1:60
	ds_read2_b32 v[16:17], v22 offset0:117 offset1:125
	ds_read2_b32 v[18:19], v22 offset0:182 offset1:190
	ds_read2_b32 v[20:21], v22 offset0:247 offset1:255
	global_store_dwordx4 v[4:5], v[0:3], off
	v_or_b32_e32 v4, s16, v78
	s_waitcnt lgkmcnt(6)
	v_cvt_pk_bf16_f32 v0, v6, v8
	v_mul_lo_u32 v6, s9, v4
	v_mad_u64_u32 v[4:5], s[18:19], s8, v4, 0
	v_add3_u32 v5, v5, s17, v6
	v_lshl_add_u64 v[4:5], v[4:5], 1, s[6:7]
	v_lshl_add_u64 v[4:5], v[4:5], 0, s[30:31]
	s_waitcnt lgkmcnt(4)
	v_cvt_pk_bf16_f32 v1, v10, v12
	s_waitcnt lgkmcnt(2)
	v_cvt_pk_bf16_f32 v2, v14, v16
	s_waitcnt lgkmcnt(0)
	v_cvt_pk_bf16_f32 v3, v18, v20
	v_lshl_add_u64 v[4:5], v[4:5], 0, v[64:65]
	global_store_dwordx4 v[4:5], v[0:3], off
	v_or_b32_e32 v4, s16, v79
	v_mul_lo_u32 v6, s9, v4
	v_mad_u64_u32 v[4:5], s[8:9], s8, v4, 0
	v_add3_u32 v5, v5, s17, v6
	v_lshl_add_u64 v[4:5], v[4:5], 1, s[6:7]
	v_lshl_add_u64 v[4:5], v[4:5], 0, s[30:31]
	v_cvt_pk_bf16_f32 v0, v7, v9
	v_cvt_pk_bf16_f32 v1, v11, v13
	v_cvt_pk_bf16_f32 v2, v15, v17
	v_cvt_pk_bf16_f32 v3, v19, v21
	v_lshl_add_u64 v[4:5], v[4:5], 0, v[64:65]
	global_store_dwordx4 v[4:5], v[0:3], off
	s_waitcnt lgkmcnt(0)
	s_cbranch_scc0 .LBB0_243

.LBB0_1122:
	s_sub_i32 s3, s2, s85
	s_cmp_lt_i32 s3, 0
	s_cselect_b64 s[4:5], -1, 0
	s_cmp_ge_i32 s2, s64
	s_cselect_b64 s[8:9], -1, 0
	s_or_b64 s[4:5], s[8:9], s[4:5]
	s_and_b64 vcc, exec, s[4:5]
	s_cbranch_vccnz .LBB0_1246
	s_lshl_b32 s3, s3, 3
	v_readlane_b32 s4, v242, 37
	s_add_i32 s3, s3, s4
	s_cmpk_gt_i32 s3, 0xcff
	s_cbranch_scc1 .LBB0_1246
	v_readlane_b32 s4, v242, 37
	s_mulk_i32 s4, 0x4200
	s_sub_i32 s5, s64, s85
	v_readlane_b32 s44, v242, 40
	s_add_i32 s10, s4, 0
	s_lshl_b32 s14, s5, 3
	v_readlane_b32 s54, v242, 50
	v_readlane_b32 s55, v242, 51
	s_add_u32 s60, s54, 0x1600000
	s_addc_u32 s61, s55, 0
	s_add_u32 s8, s76, 0x400000
	v_readlane_b32 s52, v242, 48
	s_addc_u32 s9, s77, 0
	v_readlane_b32 s53, v242, 49
	s_add_u32 s70, s52, 0x1000
	s_addc_u32 s71, s53, 0
	s_add_u32 s12, s76, 0x4280000
	v_readlane_b32 s45, v242, 41
	v_readlane_b32 s46, v242, 42
	v_readlane_b32 s47, v242, 43
	v_readlane_b32 s48, v242, 44
	v_readlane_b32 s49, v242, 45
	v_readlane_b32 s50, v242, 46
	v_readlane_b32 s51, v242, 47
	s_addc_u32 s13, s77, 0
	s_add_u32 s24, s76, 0x4080000
	v_readlane_b32 s40, v242, 3
	s_addc_u32 s25, s77, 0
	v_readlane_b32 s48, v242, 11
	v_readlane_b32 s49, v242, 12
	s_add_u32 s26, s48, 0x1000
	s_addc_u32 s27, s49, 0
	s_add_u32 s28, s76, 0x3e80000
	s_addc_u32 s29, s77, 0
	s_add_u32 s30, s76, 0x3d80000
	s_addc_u32 s31, s77, 0
	s_add_u32 s34, s76, 0x3980000
	v_readlane_b32 s46, v242, 9
	s_addc_u32 s35, s77, 0
	v_readlane_b32 s47, v242, 10
	s_add_u32 s4, s46, 0xb00000
	s_addc_u32 s5, s47, 0
	s_add_u32 s38, s76, 0x3400000
	v_readlane_b32 s44, v242, 7
	s_addc_u32 s39, s77, 0
	v_readlane_b32 s45, v242, 8
	s_add_u32 s62, s44, 0x1600000
	s_addc_u32 s63, s45, 0
	s_add_u32 s66, s76, 0x2900000
	v_readlane_b32 s42, v242, 5
	s_addc_u32 s67, s77, 0
	v_readlane_b32 s43, v242, 6
	s_add_u32 s86, s42, 0x1000
	s_addc_u32 s87, s43, 0
	s_add_u32 s88, s76, 0x2500000
	s_addc_u32 s89, s77, 0
	s_add_u32 s90, s76, 0x1f80000
	v_lshlrev_b32_e32 v0, 2, v184
	s_addc_u32 s91, s77, 0
	v_and_b32_e32 v69, 60, v0
	s_add_u32 s92, s76, 0xf00000
	v_and_b32_e32 v70, 28, v0
	v_lshlrev_b32_e32 v0, 3, v185
	v_lshrrev_b32_e32 v68, 4, v184
	v_readlane_b32 s56, v242, 52
	s_addc_u32 s93, s77, 0
	v_lshrrev_b32_e32 v71, 3, v184
	v_and_b32_e32 v0, 56, v0
	v_readlane_b32 s57, v242, 53
	s_add_u32 s72, s56, 0xb00000
	s_waitcnt lgkmcnt(0)
	v_lshl_add_u32 v1, v69, 2, s10
	v_mul_u32_u24_e32 v2, 0x104, v68
	v_mul_u32_u24_e32 v3, 0x104, v0
	v_lshlrev_b32_e32 v4, 2, v71
	s_addc_u32 s73, s57, 0
	v_mov_b32_e32 v65, 0
	v_add3_u32 v72, s10, v3, v4
	v_or_b32_e32 v73, 8, v71
	v_or_b32_e32 v74, 16, v71
	v_or_b32_e32 v75, 24, v71
	v_or_b32_e32 v76, 32, v71
	v_or_b32_e32 v77, 40, v71
	v_or_b32_e32 v78, 48, v71
	v_or_b32_e32 v79, 56, v71
	v_add_u32_e32 v80, v1, v2
	v_lshlrev_b32_e32 v64, 1, v0
	v_readlane_b32 s58, v242, 54
	v_readlane_b32 s59, v242, 55
	v_readlane_b32 s41, v242, 4
	v_readlane_b32 s50, v242, 13
	v_readlane_b32 s51, v242, 14
	v_readlane_b32 s52, v242, 15
	v_readlane_b32 s53, v242, 16
	v_readlane_b32 s54, v242, 17
	v_readlane_b32 s55, v242, 18
	s_branch .LBB0_1126
.LBB0_1125:
	s_waitcnt vmcnt(15)
	ds_write2_b32 v80, v60, v61 offset1:1
	ds_write2_b32 v80, v62, v63 offset0:2 offset1:3
	v_add_u32_e32 v60, 0x410, v80
	s_waitcnt vmcnt(14)
	ds_write2_b32 v60, v56, v57 offset1:1
	v_add_u32_e32 v56, 0x418, v80
	ds_write2_b32 v56, v58, v59 offset1:1
	v_add_u32_e32 v56, 0x820, v80
	s_waitcnt vmcnt(13)
	ds_write2_b32 v56, v52, v53 offset1:1
	v_add_u32_e32 v52, 0x828, v80
	ds_write2_b32 v52, v54, v55 offset1:1
	v_add_u32_e32 v52, 0xc30, v80
	s_waitcnt vmcnt(12)
	ds_write2_b32 v52, v48, v49 offset1:1
	v_add_u32_e32 v48, 0xc38, v80
	ds_write2_b32 v48, v50, v51 offset1:1
	v_add_u32_e32 v48, 0x1040, v80
	s_waitcnt vmcnt(11)
	ds_write2_b32 v48, v44, v45 offset1:1
	v_add_u32_e32 v44, 0x1048, v80
	ds_write2_b32 v44, v46, v47 offset1:1
	v_add_u32_e32 v44, 0x1450, v80
	s_waitcnt vmcnt(10)
	ds_write2_b32 v44, v40, v41 offset1:1
	v_add_u32_e32 v40, 0x1458, v80
	ds_write2_b32 v40, v42, v43 offset1:1
	v_add_u32_e32 v40, 0x1860, v80
	s_waitcnt vmcnt(9)
	ds_write2_b32 v40, v36, v37 offset1:1
	v_add_u32_e32 v36, 0x1868, v80
	ds_write2_b32 v36, v38, v39 offset1:1
	v_add_u32_e32 v36, 0x1c70, v80
	s_waitcnt vmcnt(8)
	ds_write2_b32 v36, v32, v33 offset1:1
	v_add_u32_e32 v32, 0x1c78, v80
	ds_write2_b32 v32, v34, v35 offset1:1
	v_add_u32_e32 v32, 0x2080, v80
	s_waitcnt vmcnt(7)
	ds_write2_b32 v32, v28, v29 offset1:1
	v_add_u32_e32 v28, 0x2088, v80
	ds_write2_b32 v28, v30, v31 offset1:1
	v_add_u32_e32 v28, 0x2490, v80
	s_waitcnt vmcnt(6)
	ds_write2_b32 v28, v24, v25 offset1:1
	v_add_u32_e32 v24, 0x2498, v80
	ds_write2_b32 v24, v26, v27 offset1:1
	v_add_u32_e32 v24, 0x28a0, v80
	s_waitcnt vmcnt(5)
	ds_write2_b32 v24, v20, v21 offset1:1
	v_add_u32_e32 v20, 0x28a8, v80
	ds_write2_b32 v20, v22, v23 offset1:1
	v_add_u32_e32 v20, 0x2cb0, v80
	s_waitcnt vmcnt(4)
	ds_write2_b32 v20, v16, v17 offset1:1
	v_add_u32_e32 v16, 0x2cb8, v80
	ds_write2_b32 v16, v18, v19 offset1:1
	v_add_u32_e32 v16, 0x30c0, v80
	s_waitcnt vmcnt(3)
	ds_write2_b32 v16, v12, v13 offset1:1
	v_add_u32_e32 v12, 0x30c8, v80
	ds_write2_b32 v12, v14, v15 offset1:1
	v_add_u32_e32 v12, 0x34d0, v80
	s_waitcnt vmcnt(2)
	ds_write2_b32 v12, v8, v9 offset1:1
	v_add_u32_e32 v8, 0x34d8, v80
	ds_write2_b32 v8, v10, v11 offset1:1
	v_add_u32_e32 v8, 0x38e0, v80
	s_waitcnt vmcnt(1)
	ds_write2_b32 v8, v4, v5 offset1:1
	v_add_u32_e32 v4, 0x38e8, v80
	ds_write2_b32 v4, v6, v7 offset1:1
	v_add_u32_e32 v4, 0x3cf0, v80
	s_waitcnt vmcnt(0)
	ds_write2_b32 v4, v0, v1 offset1:1
	v_add_u32_e32 v0, 0x3cf8, v80
	ds_write2_b32 v0, v2, v3 offset1:1
	s_waitcnt lgkmcnt(0)
	ds_read2_b32 v[4:5], v72 offset0:65 offset1:73
	ds_read2_b32 v[6:7], v72 offset1:8
	ds_read2_b32 v[8:9], v72 offset0:130 offset1:138
	ds_read2_b32 v[10:11], v72 offset0:195 offset1:203
	v_add_u32_e32 v22, 0x400, v72
	ds_read2_b32 v[12:13], v22 offset0:4 offset1:12
	ds_read2_b32 v[14:15], v22 offset0:69 offset1:77
	ds_read2_b32 v[16:17], v22 offset0:134 offset1:142
	ds_read2_b32 v[18:19], v22 offset0:199 offset1:207
	s_waitcnt lgkmcnt(6)
	v_cvt_pk_bf16_f32 v0, v6, v4
	v_or_b32_e32 v4, s15, v71
	s_ashr_i32 s10, s15, 31
	v_mul_lo_u32 v6, s41, v4
	s_mul_i32 s18, s40, s10
	v_mad_u64_u32 v[20:21], s[10:11], s40, v4, 0
	s_ashr_i32 s37, s36, 31
	v_add3_u32 v21, v21, s18, v6
	v_lshl_add_u64 v[20:21], v[20:21], 1, s[94:95]
	s_lshl_b64 s[10:11], s[36:37], 1
	v_lshl_add_u64 v[20:21], v[20:21], 0, s[10:11]
	s_waitcnt lgkmcnt(4)
	v_cvt_pk_bf16_f32 v1, v8, v10
	s_waitcnt lgkmcnt(2)
	v_cvt_pk_bf16_f32 v2, v12, v14
	s_waitcnt lgkmcnt(0)
	v_cvt_pk_bf16_f32 v3, v16, v18
	v_lshl_add_u64 v[20:21], v[20:21], 0, v[64:65]
	v_or_b32_e32 v4, s15, v73
	global_store_dwordx4 v[20:21], v[0:3], off
	v_mul_lo_u32 v6, s41, v4
	s_add_i32 s3, s3, s14
	v_cvt_pk_bf16_f32 v0, v7, v5
	v_mad_u64_u32 v[4:5], s[16:17], s40, v4, 0
	v_add3_u32 v5, v5, s18, v6
	v_lshl_add_u64 v[4:5], v[4:5], 1, s[94:95]
	v_lshl_add_u64 v[4:5], v[4:5], 0, s[10:11]
	v_cvt_pk_bf16_f32 v1, v9, v11
	v_cvt_pk_bf16_f32 v2, v13, v15
	v_cvt_pk_bf16_f32 v3, v17, v19
	v_lshl_add_u64 v[4:5], v[4:5], 0, v[64:65]
	ds_read2_b32 v[6:7], v72 offset0:16 offset1:24
	ds_read2_b32 v[8:9], v72 offset0:81 offset1:89
	ds_read2_b32 v[10:11], v72 offset0:146 offset1:154
	ds_read2_b32 v[12:13], v72 offset0:211 offset1:219
	ds_read2_b32 v[14:15], v22 offset0:20 offset1:28
	ds_read2_b32 v[16:17], v22 offset0:85 offset1:93
	ds_read2_b32 v[18:19], v22 offset0:150 offset1:158
	ds_read2_b32 v[20:21], v22 offset0:215 offset1:223
	global_store_dwordx4 v[4:5], v[0:3], off
	v_or_b32_e32 v4, s15, v74
	s_cmpk_lt_i32 s3, 0xd00
	s_waitcnt lgkmcnt(6)
	v_cvt_pk_bf16_f32 v0, v6, v8
	v_mul_lo_u32 v6, s41, v4
	v_mad_u64_u32 v[4:5], s[16:17], s40, v4, 0
	v_add3_u32 v5, v5, s18, v6
	v_lshl_add_u64 v[4:5], v[4:5], 1, s[94:95]
	v_lshl_add_u64 v[4:5], v[4:5], 0, s[10:11]
	s_waitcnt lgkmcnt(4)
	v_cvt_pk_bf16_f32 v1, v10, v12
	s_waitcnt lgkmcnt(2)
	v_cvt_pk_bf16_f32 v2, v14, v16
	s_waitcnt lgkmcnt(0)
	v_cvt_pk_bf16_f32 v3, v18, v20
	v_lshl_add_u64 v[4:5], v[4:5], 0, v[64:65]
	global_store_dwordx4 v[4:5], v[0:3], off
	v_or_b32_e32 v4, s15, v75
	v_mul_lo_u32 v6, s41, v4
	v_mad_u64_u32 v[4:5], s[16:17], s40, v4, 0
	v_add3_u32 v5, v5, s18, v6
	v_lshl_add_u64 v[4:5], v[4:5], 1, s[94:95]
	v_lshl_add_u64 v[4:5], v[4:5], 0, s[10:11]
	v_cvt_pk_bf16_f32 v0, v7, v9
	v_cvt_pk_bf16_f32 v1, v11, v13
	v_cvt_pk_bf16_f32 v2, v15, v17
	v_cvt_pk_bf16_f32 v3, v19, v21
	v_lshl_add_u64 v[4:5], v[4:5], 0, v[64:65]
	ds_read2_b32 v[6:7], v72 offset0:32 offset1:40
	ds_read2_b32 v[8:9], v72 offset0:97 offset1:105
	ds_read2_b32 v[10:11], v72 offset0:162 offset1:170
	ds_read2_b32 v[12:13], v72 offset0:227 offset1:235
	ds_read2_b32 v[14:15], v22 offset0:36 offset1:44
	ds_read2_b32 v[16:17], v22 offset0:101 offset1:109
	ds_read2_b32 v[18:19], v22 offset0:166 offset1:174
	ds_read2_b32 v[20:21], v22 offset0:231 offset1:239
	global_store_dwordx4 v[4:5], v[0:3], off
	v_or_b32_e32 v4, s15, v76
	s_waitcnt lgkmcnt(6)
	v_cvt_pk_bf16_f32 v0, v6, v8
	v_mul_lo_u32 v6, s41, v4
	v_mad_u64_u32 v[4:5], s[16:17], s40, v4, 0
	v_add3_u32 v5, v5, s18, v6
	v_lshl_add_u64 v[4:5], v[4:5], 1, s[94:95]
	v_lshl_add_u64 v[4:5], v[4:5], 0, s[10:11]
	s_waitcnt lgkmcnt(4)
	v_cvt_pk_bf16_f32 v1, v10, v12
	s_waitcnt lgkmcnt(2)
	v_cvt_pk_bf16_f32 v2, v14, v16
	s_waitcnt lgkmcnt(0)
	v_cvt_pk_bf16_f32 v3, v18, v20
	v_lshl_add_u64 v[4:5], v[4:5], 0, v[64:65]
	global_store_dwordx4 v[4:5], v[0:3], off
	v_or_b32_e32 v4, s15, v77
	v_mul_lo_u32 v6, s41, v4
	v_mad_u64_u32 v[4:5], s[16:17], s40, v4, 0
	v_add3_u32 v5, v5, s18, v6
	v_lshl_add_u64 v[4:5], v[4:5], 1, s[94:95]
	v_lshl_add_u64 v[4:5], v[4:5], 0, s[10:11]
	v_cvt_pk_bf16_f32 v0, v7, v9
	v_cvt_pk_bf16_f32 v1, v11, v13
	v_cvt_pk_bf16_f32 v2, v15, v17
	v_cvt_pk_bf16_f32 v3, v19, v21
	v_lshl_add_u64 v[4:5], v[4:5], 0, v[64:65]
	ds_read2_b32 v[6:7], v72 offset0:48 offset1:56
	ds_read2_b32 v[8:9], v72 offset0:113 offset1:121
	ds_read2_b32 v[10:11], v72 offset0:178 offset1:186
	ds_read2_b32 v[12:13], v72 offset0:243 offset1:251
	ds_read2_b32 v[14:15], v22 offset0:52 offset1:60
	ds_read2_b32 v[16:17], v22 offset0:117 offset1:125
	ds_read2_b32 v[18:19], v22 offset0:182 offset1:190
	ds_read2_b32 v[20:21], v22 offset0:247 offset1:255
	global_store_dwordx4 v[4:5], v[0:3], off
	v_or_b32_e32 v4, s15, v78
	s_waitcnt lgkmcnt(6)
	v_cvt_pk_bf16_f32 v0, v6, v8
	v_mul_lo_u32 v6, s41, v4
	v_mad_u64_u32 v[4:5], s[16:17], s40, v4, 0
	v_add3_u32 v5, v5, s18, v6
	v_lshl_add_u64 v[4:5], v[4:5], 1, s[94:95]
	v_lshl_add_u64 v[4:5], v[4:5], 0, s[10:11]
	s_waitcnt lgkmcnt(4)
	v_cvt_pk_bf16_f32 v1, v10, v12
	s_waitcnt lgkmcnt(2)
	v_cvt_pk_bf16_f32 v2, v14, v16
	s_waitcnt lgkmcnt(0)
	v_cvt_pk_bf16_f32 v3, v18, v20
	v_lshl_add_u64 v[4:5], v[4:5], 0, v[64:65]
	global_store_dwordx4 v[4:5], v[0:3], off
	v_or_b32_e32 v4, s15, v79
	v_mul_lo_u32 v6, s41, v4
	v_mad_u64_u32 v[4:5], s[16:17], s40, v4, 0
	v_add3_u32 v5, v5, s18, v6
	v_lshl_add_u64 v[4:5], v[4:5], 1, s[94:95]
	v_lshl_add_u64 v[4:5], v[4:5], 0, s[10:11]
	v_cvt_pk_bf16_f32 v0, v7, v9
	v_cvt_pk_bf16_f32 v1, v11, v13
	v_cvt_pk_bf16_f32 v2, v15, v17
	v_cvt_pk_bf16_f32 v3, v19, v21
	v_lshl_add_u64 v[4:5], v[4:5], 0, v[64:65]
	global_store_dwordx4 v[4:5], v[0:3], off
	s_waitcnt lgkmcnt(0)
	s_cbranch_scc0 .LBB0_1246
.LBB0_1126:
	s_mov_b32 s17, s3
	s_mov_b32 s18, 3
	s_branch .LBB0_1129
